# attention un-masked tile body: score - key-term subtractions and exp-argument fmas paired into v_pk_add_f32 / v_pk_fma_f32 (31 fewer VALU per tile, same f32 operations)
# baseline (speedup 1.0000x reference)
.Latt_nomask:
	ds_read_b128 v[32:35], v101 offset:8192
	ds_read_b128 v[36:39], v101 offset:8224
	s_waitcnt lgkmcnt(1)
	v_mfma_f32_32x32x16_bf16 v[48:63], v[32:35], v[72:75], v[144:159]
	ds_read_b128 v[32:35], v101 offset:8256
	ds_read_b128 v[106:109], v101 offset:8288
	s_mov_b32 s12, 0xf149f2ca
	s_waitcnt lgkmcnt(2)
	v_mfma_f32_32x32x16_bf16 v[48:63], v[36:39], v[64:67], v[48:63]
	s_waitcnt lgkmcnt(1)
	v_mfma_f32_32x32x16_bf16 v[48:63], v[32:35], v[68:71], v[48:63]
	ds_read_b128 v[32:35], v101 offset:12800
	ds_read_b128 v[110:113], v101 offset:12832
	ds_read_b128 v[114:117], v101 offset:12864
	ds_read_b128 v[118:121], v101 offset:12896
	ds_read_b128 v[122:125], v104
	ds_read_b128 v[126:129], v104 offset:32
	s_waitcnt lgkmcnt(6)
	v_mfma_f32_32x32x16_bf16 v[48:63], v[106:109], v[76:79], v[48:63]
	s_waitcnt lgkmcnt(5)
	v_mfma_f32_32x32x16_bf16 v[32:47], v[32:35], v[72:75], v[144:159]
	s_nop 9
	s_waitcnt lgkmcnt(1)
	v_pk_add_f32 v[106:107], v[48:49], v[122:123] neg_lo:[0,1] neg_hi:[0,1]
	v_pk_add_f32 v[108:109], v[50:51], v[124:125] neg_lo:[0,1] neg_hi:[0,1]
	s_waitcnt lgkmcnt(0)
	v_pk_add_f32 v[122:123], v[52:53], v[126:127] neg_lo:[0,1] neg_hi:[0,1]
	v_max3_f32 v48, v106, s12, v107
	v_mfma_f32_32x32x16_bf16 v[32:47], v[110:113], v[64:67], v[32:47]
	v_max3_f32 v48, v48, v108, v109
	v_pk_add_f32 v[110:111], v[54:55], v[128:129] neg_lo:[0,1] neg_hi:[0,1]
	v_max3_f32 v48, v48, v122, v123
	v_max3_f32 v112, v48, v110, v111
	ds_read_b128 v[48:51], v104 offset:64
	ds_read_b128 v[52:55], v104 offset:96
	v_mfma_f32_32x32x16_bf16 v[32:47], v[114:117], v[68:71], v[32:47]
	s_waitcnt lgkmcnt(1)
	v_pk_add_f32 v[56:57], v[56:57], v[48:49] neg_lo:[0,1] neg_hi:[0,1]
	s_nop 0
	v_max3_f32 v48, v112, v56, v57
	v_pk_add_f32 v[58:59], v[58:59], v[50:51] neg_lo:[0,1] neg_hi:[0,1]
	s_waitcnt lgkmcnt(0)
	v_pk_add_f32 v[60:61], v[60:61], v[52:53] neg_lo:[0,1] neg_hi:[0,1]
	v_max3_f32 v48, v48, v58, v59
	v_mfma_f32_32x32x16_bf16 v[32:47], v[118:121], v[76:79], v[32:47]
	v_max3_f32 v52, v48, v60, v61
	v_pk_add_f32 v[62:63], v[62:63], v[54:55] neg_lo:[0,1] neg_hi:[0,1]
	s_nop 6
	ds_read_b128 v[48:51], v104 offset:128
	v_max3_f32 v112, v52, v62, v63
	ds_read_b128 v[52:55], v104 offset:160
	s_waitcnt lgkmcnt(1)
	v_pk_add_f32 v[48:49], v[32:33], v[48:49] neg_lo:[0,1] neg_hi:[0,1]
	s_nop 0
	v_max3_f32 v32, v112, v48, v49
	v_pk_add_f32 v[50:51], v[34:35], v[50:51] neg_lo:[0,1] neg_hi:[0,1]
	s_waitcnt lgkmcnt(0)
	v_pk_add_f32 v[52:53], v[36:37], v[52:53] neg_lo:[0,1] neg_hi:[0,1]
	v_max3_f32 v32, v32, v50, v51
	s_nop 0
	v_max3_f32 v36, v32, v52, v53
	s_nop 0
	v_pk_add_f32 v[54:55], v[38:39], v[54:55] neg_lo:[0,1] neg_hi:[0,1]
	s_nop 1
	ds_read_b128 v[32:35], v104 offset:192
	v_max3_f32 v112, v36, v54, v55
	ds_read_b128 v[36:39], v104 offset:224
	s_waitcnt lgkmcnt(1)
	v_pk_add_f32 v[32:33], v[40:41], v[32:33] neg_lo:[0,1] neg_hi:[0,1]
	v_pk_add_f32 v[34:35], v[42:43], v[34:35] neg_lo:[0,1] neg_hi:[0,1]
	s_waitcnt lgkmcnt(0)
	v_pk_add_f32 v[36:37], v[44:45], v[36:37] neg_lo:[0,1] neg_hi:[0,1]
	v_max3_f32 v40, v112, v32, v33
	v_max3_f32 v40, v40, v34, v35
	s_nop 0
	v_mov_b32_e32 v112, v37
	v_max3_f32 v37, v40, v36, v112
	s_nop 1
	v_pk_add_f32 v[46:47], v[46:47], v[38:39] neg_lo:[0,1] neg_hi:[0,1]
	s_nop 1
	v_max3_f32 v37, v37, v46, v47
	ds_bpermute_b32 v38, v99, v37
	s_waitcnt lgkmcnt(0)
	v_max3_f32 v113, v105, v37, v38
	s_mov_b32 s99, 0x3fb8aa3b
	s_mov_b32 s98, 0x3fb8aa3b
	v_mul_f32_e32 v250, 0xbfb8aa3b, v113
	v_pk_fma_f32 v[106:107], v[106:107], s[98:99], v[250:251] op_sel_hi:[1,0,0]
	s_nop 0
	v_exp_f32_e32 v38, v106
	v_exp_f32_e32 v39, v107
	v_pk_fma_f32 v[108:109], v[108:109], s[98:99], v[250:251] op_sel_hi:[1,0,0]
	s_nop 0
	v_exp_f32_e32 v40, v108
	v_exp_f32_e32 v41, v109
	v_pk_fma_f32 v[122:123], v[122:123], s[98:99], v[250:251] op_sel_hi:[1,0,0]
	v_add_f32_e32 v42, 0, v38
	v_exp_f32_e32 v43, v122
	v_sub_f32_e32 v37, v105, v113
	v_add_f32_e32 v42, v39, v42
	v_exp_f32_e32 v44, v123
	v_pk_fma_f32 v[110:111], v[110:111], s[98:99], v[250:251] op_sel_hi:[1,0,0]
	v_add_f32_e32 v42, v40, v42
	v_exp_f32_e32 v45, v110
	v_add_f32_e32 v42, v41, v42
	v_exp_f32_e32 v105, v111
	v_pk_fma_f32 v[56:57], v[56:57], s[98:99], v[250:251] op_sel_hi:[1,0,0]
	v_add_f32_e32 v42, v43, v42
	v_exp_f32_e32 v56, v56
	v_add_f32_e32 v42, v44, v42
	v_exp_f32_e32 v57, v57
	v_pk_fma_f32 v[58:59], v[58:59], s[98:99], v[250:251] op_sel_hi:[1,0,0]
	v_add_f32_e32 v42, v45, v42
	v_exp_f32_e32 v58, v58
	v_add_f32_e32 v42, v105, v42
	v_exp_f32_e32 v59, v59
	v_pk_fma_f32 v[60:61], v[60:61], s[98:99], v[250:251] op_sel_hi:[1,0,0]
	v_add_f32_e32 v42, v56, v42
	v_exp_f32_e32 v60, v60
	v_add_f32_e32 v42, v57, v42
	v_exp_f32_e32 v61, v61
	v_pk_fma_f32 v[62:63], v[62:63], s[98:99], v[250:251] op_sel_hi:[1,0,0]
	v_add_f32_e32 v42, v58, v42
	v_exp_f32_e32 v62, v62
	v_add_f32_e32 v42, v59, v42
	v_exp_f32_e32 v63, v63
	v_add_f32_e32 v42, v60, v42
	v_add_f32_e32 v42, v61, v42
	v_add_f32_e32 v42, v62, v42
	v_add_f32_e32 v106, v63, v42
	v_pk_fma_f32 v[48:49], v[48:49], s[98:99], v[250:251] op_sel_hi:[1,0,0]
	s_nop 0
	v_exp_f32_e32 v48, v48
	v_pk_fma_f32 v[32:33], v[32:33], s[98:99], v[250:251] op_sel_hi:[1,0,0]
	s_nop 0
	v_exp_f32_e32 v107, v32
	v_exp_f32_e32 v49, v49
	v_pk_fma_f32 v[50:51], v[50:51], s[98:99], v[250:251] op_sel_hi:[1,0,0]
	v_exp_f32_e32 v33, v33
	v_exp_f32_e32 v50, v50
	v_pk_fma_f32 v[34:35], v[34:35], s[98:99], v[250:251] op_sel_hi:[1,0,0]
	s_nop 0
	v_exp_f32_e32 v108, v34
	v_mul_f32_e32 v37, 0x3fb8aa3b, v37
	v_exp_f32_e32 v51, v51
	v_fma_f32 v34, v36, s99, v250
	v_pk_fma_f32 v[52:53], v[52:53], s[98:99], v[250:251] op_sel_hi:[1,0,0]
	v_exp_f32_e32 v109, v35
	v_exp_f32_e32 v32, v37
	v_exp_f32_e32 v110, v34
	ds_read2_b64 v[34:37], v102 offset0:128 offset1:130
	v_exp_f32_e32 v52, v52
	v_exp_f32_e32 v53, v53
	v_pk_fma_f32 v[54:55], v[54:55], s[98:99], v[250:251] op_sel_hi:[1,0,0]
	s_nop 0
	v_exp_f32_e32 v54, v54
	v_exp_f32_e32 v55, v55
	v_cvt_pk_bf16_f32 v38, v38, v39
	v_cvt_pk_bf16_f32 v39, v40, v41
	v_cvt_pk_bf16_f32 v40, v43, v44
	v_cvt_pk_bf16_f32 v41, v45, v105
	ds_read2_b64 v[42:45], v103 offset0:192 offset1:194
	v_pk_mul_f32 v[30:31], v[30:31], v[32:33] op_sel_hi:[1,0]
	v_pk_mul_f32 v[28:29], v[28:29], v[32:33] op_sel_hi:[1,0]
	v_pk_mul_f32 v[26:27], v[26:27], v[32:33] op_sel_hi:[1,0]
	v_pk_mul_f32 v[24:25], v[24:25], v[32:33] op_sel_hi:[1,0]
	v_pk_mul_f32 v[22:23], v[22:23], v[32:33] op_sel_hi:[1,0]
	v_pk_mul_f32 v[20:21], v[20:21], v[32:33] op_sel_hi:[1,0]
	v_pk_mul_f32 v[18:19], v[18:19], v[32:33] op_sel_hi:[1,0]
	v_pk_mul_f32 v[16:17], v[16:17], v[32:33] op_sel_hi:[1,0]
	v_pk_mul_f32 v[14:15], v[14:15], v[32:33] op_sel_hi:[1,0]
	v_pk_mul_f32 v[12:13], v[12:13], v[32:33] op_sel_hi:[1,0]
	s_waitcnt lgkmcnt(1)
	v_mfma_f32_32x32x16_bf16 v[16:31], v[34:37], v[38:41], v[16:31]
	ds_read2_b64 v[34:37], v102 offset0:132 offset1:134
	v_mul_f32_e64 v10, v10, v32
	v_mul_f32_e64 v11, v11, v32
	v_mul_f32_e64 v8, v8, v32
	v_mul_f32_e64 v9, v9, v32
	v_pk_mul_f32 v[6:7], v[6:7], v[32:33] op_sel_hi:[1,0]
	v_pk_mul_f32 v[4:5], v[4:5], v[32:33] op_sel_hi:[1,0]
	v_pk_mul_f32 v[2:3], v[2:3], v[32:33] op_sel_hi:[1,0]
	v_pk_mul_f32 v[0:1], v[0:1], v[32:33] op_sel_hi:[1,0]
	s_waitcnt lgkmcnt(1)
	s_nop 0
	v_mfma_f32_32x32x16_bf16 v[0:15], v[42:45], v[38:41], v[0:15]
	v_fma_f32 v105, v112, s99, v250
	v_cvt_pk_bf16_f32 v38, v56, v57
	v_cvt_pk_bf16_f32 v39, v58, v59
	v_cvt_pk_bf16_f32 v40, v60, v61
	v_cvt_pk_bf16_f32 v41, v62, v63
	ds_read2_b64 v[42:45], v103 offset0:196 offset1:198
	v_add_f32_e32 v57, v48, v106
	s_waitcnt lgkmcnt(1)
	v_mfma_f32_32x32x16_bf16 v[16:31], v[34:37], v[38:41], v[16:31]
	v_pk_fma_f32 v[46:47], v[46:47], s[98:99], v[250:251] op_sel_hi:[1,0,0]
	s_nop 0
	v_exp_f32_e32 v46, v46
	ds_read2_b64 v[34:37], v102 offset0:136 offset1:138
	v_exp_f32_e32 v56, v105
	s_waitcnt lgkmcnt(1)
	v_mfma_f32_32x32x16_bf16 v[0:15], v[42:45], v[38:41], v[0:15]
	ds_read2_b64 v[42:45], v103 offset0:200 offset1:202
	v_cvt_pk_bf16_f32 v38, v48, v49
	v_cvt_pk_bf16_f32 v39, v50, v51
	v_cvt_pk_bf16_f32 v40, v52, v53
	v_cvt_pk_bf16_f32 v41, v54, v55
	v_exp_f32_e32 v47, v47
	v_mov_b32_e32 v105, v113
	s_waitcnt lgkmcnt(1)
	v_mfma_f32_32x32x16_bf16 v[16:31], v[34:37], v[38:41], v[16:31]
	v_add_f32_e32 v34, v49, v57
	v_add_f32_e32 v34, v50, v34
	v_add_f32_e32 v34, v51, v34
	v_add_f32_e32 v34, v52, v34
	v_add_f32_e32 v34, v53, v34
	v_add_f32_e32 v48, v54, v34
	ds_read2_b64 v[34:37], v102 offset0:140 offset1:142
	s_waitcnt lgkmcnt(1)
	v_mfma_f32_32x32x16_bf16 v[0:15], v[42:45], v[38:41], v[0:15]
	ds_read2_b64 v[42:45], v103 offset0:204 offset1:206
	v_add_f32_e32 v38, v55, v48
	v_add_f32_e32 v48, v107, v38
	v_cvt_pk_bf16_f32 v38, v107, v33
	v_cvt_pk_bf16_f32 v39, v108, v109
	v_cvt_pk_bf16_f32 v40, v110, v56
	v_cvt_pk_bf16_f32 v41, v46, v47
	v_add_f32_e32 v33, v33, v48
	v_add_f32_e32 v33, v108, v33
	s_waitcnt lgkmcnt(1)
	v_mfma_f32_32x32x16_bf16 v[16:31], v[34:37], v[38:41], v[16:31]
	v_add_f32_e32 v33, v109, v33
	v_add_f32_e32 v33, v110, v33
	v_add_f32_e32 v33, v56, v33
	v_add_f32_e32 v33, v46, v33
	v_add_f32_e32 v33, v47, v33
	v_fmac_f32_e32 v33, v100, v32
	v_mov_b32_e32 v100, v33
	s_waitcnt lgkmcnt(0)
	v_mfma_f32_32x32x16_bf16 v[0:15], v[42:45], v[38:41], v[0:15]
	s_branch .LBB0_934
